# speedup vs baseline: 1.0178x; 1.0047x over previous
; __global__ void __launch_bounds__(NTHREADS, 2) fwd_megakernel(Params p_arg) {
;     ...
;       const float* gt = modl + (size_t)(brow >> 12) * 6144 + 2048;
; #pragma unroll
;       for (int n = 0; n < 4; ++n) {
;         const float4 g4 = *(const float4*)(gt + cofs + n * 16);
; #pragma unroll
;         for (int m = 0; m < 8; ++m) {
;           const size_t row = (size_t)brow + wr * 128 + m * 16 + fr;
;           float4 xo = *(const float4*)(xin + row * 1024 + cofs + n * 16);
;           xo.x += g4.x * acc[m][n][0]; xo.y += g4.y * acc[m][n][1]; xo.z += g4.z * acc[m][n][2]; xo.w += g4.w * acc[m][n][3];
;           *(float4*)(pk->out + row * 1024 + cofs + n * 16) = xo;
;         }
;         if (n == 1) __builtin_amdgcn_sched_barrier(0);
;       }
.LBB0_454:
	s_ashr_i32 s0, s47, 4
	v_or_b32_e32 v106, s14, v154
	s_mul_hi_i32 s1, s0, 0x6000
	s_mulk_i32 s0, 0x6000
	s_add_u32 s0, s28, s0
	v_ashrrev_i32_e32 v107, 31, v106
	s_addc_u32 s1, s37, s1
	v_lshlrev_b64 v[106:107], 2, v[106:107]
	v_lshl_add_u64 v[108:109], s[0:1], 0, v[106:107]
	s_mov_b64 s[0:1], 0x7102000
	v_lshl_add_u64 v[140:141], v[108:109], 0, s[0:1]
	s_load_dwordx2 s[0:1], s[4:5], 0x90
	v_lshl_add_u64 v[136:137], v[134:135], 0, s[12:13]
	v_lshl_add_u64 v[144:145], s[10:11], 0, v[106:107]
	v_lshlrev_b64 v[136:137], 12, v[136:137]
	v_lshl_add_u64 v[146:147], v[144:145], 0, v[136:137]
	s_waitcnt lgkmcnt(0)
	v_lshl_add_u64 v[138:139], s[0:1], 0, v[106:107]
	s_mov_b32 s0, 0x7102000
	v_add_co_u32_e32 v106, vcc, s0, v108
	v_lshl_add_u64 v[142:143], v[138:139], 0, v[136:137]
	s_nop 0
	v_addc_co_u32_e32 v107, vcc, 0, v109, vcc
	v_lshl_add_u64 v[180:181], v[144:145], 0, v[136:137]
	v_or_b32_e32 v196, 0x10000, v136
	v_mov_b32_e32 v197, v137
	v_lshl_add_u64 v[182:183], v[144:145], 0, v[196:197]
	v_or_b32_e32 v196, 0x20000, v136
	v_mov_b32_e32 v197, v137
	v_lshl_add_u64 v[184:185], v[144:145], 0, v[196:197]
	v_or_b32_e32 v196, 0x30000, v136
	v_mov_b32_e32 v197, v137
	v_lshl_add_u64 v[186:187], v[144:145], 0, v[196:197]
	v_or_b32_e32 v196, 0x40000, v136
	v_mov_b32_e32 v197, v137
	v_lshl_add_u64 v[188:189], v[144:145], 0, v[196:197]
	v_or_b32_e32 v196, 0x50000, v136
	v_mov_b32_e32 v197, v137
	v_lshl_add_u64 v[190:191], v[144:145], 0, v[196:197]
	v_or_b32_e32 v196, 0x60000, v136
	v_mov_b32_e32 v197, v137
	v_lshl_add_u64 v[192:193], v[144:145], 0, v[196:197]
	v_or_b32_e32 v196, 0x70000, v136
	v_mov_b32_e32 v197, v137
	v_lshl_add_u64 v[194:195], v[144:145], 0, v[196:197]
	v_sub_co_u32_e32 v198, vcc, v138, v144
	s_nop 1
	v_subb_co_u32_e32 v199, vcc, v139, v145, vcc
	global_load_dwordx4 v[200:203], v[140:141], off
	global_load_dwordx4 v[204:207], v[140:141], off offset:64
	global_load_dwordx4 v[208:211], v[140:141], off offset:128
	global_load_dwordx4 v[212:215], v[140:141], off offset:192
	global_load_dwordx4 v[216:219], v[180:181], off
	global_load_dwordx4 v[220:223], v[182:183], off
	global_load_dwordx4 v[224:227], v[184:185], off
	global_load_dwordx4 v[228:231], v[186:187], off
	global_load_dwordx4 v[232:235], v[188:189], off
	global_load_dwordx4 v[236:239], v[190:191], off
	global_load_dwordx4 v[240:243], v[192:193], off
	global_load_dwordx4 v[244:247], v[194:195], off
	s_waitcnt vmcnt(7)
	v_pk_fma_f32 v[130:131], v[200:201], v[130:131], v[216:217]
	v_pk_fma_f32 v[132:133], v[202:203], v[132:133], v[218:219]
	v_lshl_add_u64 v[196:197], v[180:181], 0, v[198:199]
	global_store_dwordx4 v[196:197], v[130:133], off
	global_load_dwordx4 v[216:219], v[180:181], off offset:64
	s_waitcnt vmcnt(8)
	v_pk_fma_f32 v[126:127], v[200:201], v[126:127], v[220:221]
	v_pk_fma_f32 v[128:129], v[202:203], v[128:129], v[222:223]
	v_lshl_add_u64 v[196:197], v[182:183], 0, v[198:199]
	global_store_dwordx4 v[196:197], v[126:129], off
	global_load_dwordx4 v[220:223], v[182:183], off offset:64
	s_waitcnt vmcnt(9)
	v_pk_fma_f32 v[122:123], v[200:201], v[122:123], v[224:225]
	v_pk_fma_f32 v[124:125], v[202:203], v[124:125], v[226:227]
	v_lshl_add_u64 v[196:197], v[184:185], 0, v[198:199]
	global_store_dwordx4 v[196:197], v[122:125], off
	global_load_dwordx4 v[224:227], v[184:185], off offset:64
	s_waitcnt vmcnt(10)
	v_pk_fma_f32 v[114:115], v[200:201], v[114:115], v[228:229]
	v_pk_fma_f32 v[116:117], v[202:203], v[116:117], v[230:231]
	v_lshl_add_u64 v[196:197], v[186:187], 0, v[198:199]
	global_store_dwordx4 v[196:197], v[114:117], off
	global_load_dwordx4 v[228:231], v[186:187], off offset:64
	s_waitcnt vmcnt(11)
	v_pk_fma_f32 v[118:119], v[200:201], v[118:119], v[232:233]
	v_pk_fma_f32 v[120:121], v[202:203], v[120:121], v[234:235]
	v_lshl_add_u64 v[196:197], v[188:189], 0, v[198:199]
	global_store_dwordx4 v[196:197], v[118:121], off
	global_load_dwordx4 v[232:235], v[188:189], off offset:64
	s_waitcnt vmcnt(12)
	v_pk_fma_f32 v[110:111], v[200:201], v[110:111], v[236:237]
	v_pk_fma_f32 v[112:113], v[202:203], v[112:113], v[238:239]
	v_lshl_add_u64 v[196:197], v[190:191], 0, v[198:199]
	global_store_dwordx4 v[196:197], v[110:113], off
	global_load_dwordx4 v[236:239], v[190:191], off offset:64
	s_waitcnt vmcnt(13)
	v_pk_fma_f32 v[102:103], v[200:201], v[102:103], v[240:241]
	v_pk_fma_f32 v[104:105], v[202:203], v[104:105], v[242:243]
	v_lshl_add_u64 v[196:197], v[192:193], 0, v[198:199]
	global_store_dwordx4 v[196:197], v[102:105], off
	global_load_dwordx4 v[240:243], v[192:193], off offset:64
	s_waitcnt vmcnt(14)
	v_pk_fma_f32 v[98:99], v[200:201], v[98:99], v[244:245]
	v_pk_fma_f32 v[100:101], v[202:203], v[100:101], v[246:247]
	v_lshl_add_u64 v[196:197], v[194:195], 0, v[198:199]
	global_store_dwordx4 v[196:197], v[98:101], off
	global_load_dwordx4 v[244:247], v[194:195], off offset:64
	s_waitcnt vmcnt(14)
	v_pk_fma_f32 v[94:95], v[204:205], v[94:95], v[216:217]
	v_pk_fma_f32 v[96:97], v[206:207], v[96:97], v[218:219]
	v_lshl_add_u64 v[196:197], v[180:181], 0, v[198:199]
	global_store_dwordx4 v[196:197], v[94:97], off offset:64
	global_load_dwordx4 v[216:219], v[180:181], off offset:128
	s_waitcnt vmcnt(14)
	v_pk_fma_f32 v[90:91], v[204:205], v[90:91], v[220:221]
	v_pk_fma_f32 v[92:93], v[206:207], v[92:93], v[222:223]
	v_lshl_add_u64 v[196:197], v[182:183], 0, v[198:199]
	global_store_dwordx4 v[196:197], v[90:93], off offset:64
	global_load_dwordx4 v[220:223], v[182:183], off offset:128
	s_waitcnt vmcnt(14)
; __global__ void __launch_bounds__(NTHREADS, 2) fwd_megakernel(Params p_arg) {
;     ...
;       const float* gt = modl + (size_t)(brow >> 12) * 6144 + 2048;
; #pragma unroll
;       for (int n = 0; n < 4; ++n) {
;         const float4 g4 = *(const float4*)(gt + cofs + n * 16);
; #pragma unroll
;         for (int m = 0; m < 8; ++m) {
;           const size_t row = (size_t)brow + wr * 128 + m * 16 + fr;
;           float4 xo = *(const float4*)(xin + row * 1024 + cofs + n * 16);
;           xo.x += g4.x * acc[m][n][0]; xo.y += g4.y * acc[m][n][1]; xo.z += g4.z * acc[m][n][2]; xo.w += g4.w * acc[m][n][3];
;           *(float4*)(pk->out + row * 1024 + cofs + n * 16) = xo;
;         }
;         if (n == 1) __builtin_amdgcn_sched_barrier(0);
;       }
	v_pk_fma_f32 v[86:87], v[204:205], v[86:87], v[224:225]
	v_pk_fma_f32 v[88:89], v[206:207], v[88:89], v[226:227]
	v_lshl_add_u64 v[196:197], v[184:185], 0, v[198:199]
	global_store_dwordx4 v[196:197], v[86:89], off offset:64
	global_load_dwordx4 v[224:227], v[184:185], off offset:128
	s_waitcnt vmcnt(14)
	v_pk_fma_f32 v[78:79], v[204:205], v[78:79], v[228:229]
	v_pk_fma_f32 v[80:81], v[206:207], v[80:81], v[230:231]
	v_lshl_add_u64 v[196:197], v[186:187], 0, v[198:199]
	global_store_dwordx4 v[196:197], v[78:81], off offset:64
	global_load_dwordx4 v[228:231], v[186:187], off offset:128
	s_waitcnt vmcnt(14)
	v_pk_fma_f32 v[82:83], v[204:205], v[82:83], v[232:233]
	v_pk_fma_f32 v[84:85], v[206:207], v[84:85], v[234:235]
	v_lshl_add_u64 v[196:197], v[188:189], 0, v[198:199]
	global_store_dwordx4 v[196:197], v[82:85], off offset:64
	global_load_dwordx4 v[232:235], v[188:189], off offset:128
	s_waitcnt vmcnt(14)
	v_pk_fma_f32 v[74:75], v[204:205], v[74:75], v[236:237]
	v_pk_fma_f32 v[76:77], v[206:207], v[76:77], v[238:239]
	v_lshl_add_u64 v[196:197], v[190:191], 0, v[198:199]
	global_store_dwordx4 v[196:197], v[74:77], off offset:64
	global_load_dwordx4 v[236:239], v[190:191], off offset:128
	s_waitcnt vmcnt(14)
	v_pk_fma_f32 v[70:71], v[204:205], v[70:71], v[240:241]
	v_pk_fma_f32 v[72:73], v[206:207], v[72:73], v[242:243]
	v_lshl_add_u64 v[196:197], v[192:193], 0, v[198:199]
	global_store_dwordx4 v[196:197], v[70:73], off offset:64
	global_load_dwordx4 v[240:243], v[192:193], off offset:128
	s_waitcnt vmcnt(14)
	v_pk_fma_f32 v[66:67], v[204:205], v[66:67], v[244:245]
	v_pk_fma_f32 v[68:69], v[206:207], v[68:69], v[246:247]
	v_lshl_add_u64 v[196:197], v[194:195], 0, v[198:199]
	global_store_dwordx4 v[196:197], v[66:69], off offset:64
	global_load_dwordx4 v[244:247], v[194:195], off offset:128
	s_waitcnt vmcnt(14)
	v_pk_fma_f32 v[62:63], v[208:209], v[62:63], v[216:217]
	v_pk_fma_f32 v[64:65], v[210:211], v[64:65], v[218:219]
	v_lshl_add_u64 v[196:197], v[180:181], 0, v[198:199]
	global_store_dwordx4 v[196:197], v[62:65], off offset:128
	global_load_dwordx4 v[216:219], v[180:181], off offset:192
	s_waitcnt vmcnt(14)
	v_pk_fma_f32 v[58:59], v[208:209], v[58:59], v[220:221]
	v_pk_fma_f32 v[60:61], v[210:211], v[60:61], v[222:223]
	v_lshl_add_u64 v[196:197], v[182:183], 0, v[198:199]
	global_store_dwordx4 v[196:197], v[58:61], off offset:128
	global_load_dwordx4 v[220:223], v[182:183], off offset:192
	s_waitcnt vmcnt(14)
	v_pk_fma_f32 v[50:51], v[208:209], v[50:51], v[224:225]
	v_pk_fma_f32 v[52:53], v[210:211], v[52:53], v[226:227]
	v_lshl_add_u64 v[196:197], v[184:185], 0, v[198:199]
	global_store_dwordx4 v[196:197], v[50:53], off offset:128
	global_load_dwordx4 v[224:227], v[184:185], off offset:192
	s_waitcnt vmcnt(14)
	v_pk_fma_f32 v[42:43], v[208:209], v[42:43], v[228:229]
	v_pk_fma_f32 v[44:45], v[210:211], v[44:45], v[230:231]
	v_lshl_add_u64 v[196:197], v[186:187], 0, v[198:199]
	global_store_dwordx4 v[196:197], v[42:45], off offset:128
	global_load_dwordx4 v[228:231], v[186:187], off offset:192
	s_waitcnt vmcnt(14)
	v_pk_fma_f32 v[54:55], v[208:209], v[54:55], v[232:233]
	v_pk_fma_f32 v[56:57], v[210:211], v[56:57], v[234:235]
	v_lshl_add_u64 v[196:197], v[188:189], 0, v[198:199]
	global_store_dwordx4 v[196:197], v[54:57], off offset:128
	global_load_dwordx4 v[232:235], v[188:189], off offset:192
	s_waitcnt vmcnt(14)
	v_pk_fma_f32 v[46:47], v[208:209], v[46:47], v[236:237]
	v_pk_fma_f32 v[48:49], v[210:211], v[48:49], v[238:239]
	v_lshl_add_u64 v[196:197], v[190:191], 0, v[198:199]
	global_store_dwordx4 v[196:197], v[46:49], off offset:128
	global_load_dwordx4 v[236:239], v[190:191], off offset:192
	s_waitcnt vmcnt(14)
	v_pk_fma_f32 v[38:39], v[208:209], v[38:39], v[240:241]
	v_pk_fma_f32 v[40:41], v[210:211], v[40:41], v[242:243]
	v_lshl_add_u64 v[196:197], v[192:193], 0, v[198:199]
	global_store_dwordx4 v[196:197], v[38:41], off offset:128
	global_load_dwordx4 v[240:243], v[192:193], off offset:192
	s_waitcnt vmcnt(14)
	v_pk_fma_f32 v[34:35], v[208:209], v[34:35], v[244:245]
	v_pk_fma_f32 v[36:37], v[210:211], v[36:37], v[246:247]
	v_lshl_add_u64 v[196:197], v[194:195], 0, v[198:199]
	global_store_dwordx4 v[196:197], v[34:37], off offset:128
	global_load_dwordx4 v[244:247], v[194:195], off offset:192
	s_waitcnt vmcnt(14)
	v_pk_fma_f32 v[30:31], v[212:213], v[30:31], v[216:217]
	v_pk_fma_f32 v[32:33], v[214:215], v[32:33], v[218:219]
	v_lshl_add_u64 v[196:197], v[180:181], 0, v[198:199]
	global_store_dwordx4 v[196:197], v[30:33], off offset:192
	s_waitcnt vmcnt(13)
	v_pk_fma_f32 v[26:27], v[212:213], v[26:27], v[220:221]
	v_pk_fma_f32 v[28:29], v[214:215], v[28:29], v[222:223]
	v_lshl_add_u64 v[196:197], v[182:183], 0, v[198:199]
	global_store_dwordx4 v[196:197], v[26:29], off offset:192
	s_waitcnt vmcnt(12)
	v_pk_fma_f32 v[18:19], v[212:213], v[18:19], v[224:225]
	v_pk_fma_f32 v[20:21], v[214:215], v[20:21], v[226:227]
	v_lshl_add_u64 v[196:197], v[184:185], 0, v[198:199]
	global_store_dwordx4 v[196:197], v[18:21], off offset:192
	s_waitcnt vmcnt(11)
	v_pk_fma_f32 v[10:11], v[212:213], v[10:11], v[228:229]
	v_pk_fma_f32 v[12:13], v[214:215], v[12:13], v[230:231]
	v_lshl_add_u64 v[196:197], v[186:187], 0, v[198:199]
	global_store_dwordx4 v[196:197], v[10:13], off offset:192
	s_waitcnt vmcnt(10)
	v_pk_fma_f32 v[22:23], v[212:213], v[22:23], v[232:233]
	v_pk_fma_f32 v[24:25], v[214:215], v[24:25], v[234:235]
	v_lshl_add_u64 v[196:197], v[188:189], 0, v[198:199]
	global_store_dwordx4 v[196:197], v[22:25], off offset:192
	s_waitcnt vmcnt(9)
	v_pk_fma_f32 v[14:15], v[212:213], v[14:15], v[236:237]
	v_pk_fma_f32 v[16:17], v[214:215], v[16:17], v[238:239]
	v_lshl_add_u64 v[196:197], v[190:191], 0, v[198:199]
	global_store_dwordx4 v[196:197], v[14:17], off offset:192
	s_waitcnt vmcnt(8)
	v_pk_fma_f32 v[6:7], v[212:213], v[6:7], v[240:241]
	v_pk_fma_f32 v[8:9], v[214:215], v[8:9], v[242:243]
	v_lshl_add_u64 v[196:197], v[192:193], 0, v[198:199]
	global_store_dwordx4 v[196:197], v[6:9], off offset:192
	s_waitcnt vmcnt(7)
	v_pk_fma_f32 v[2:3], v[212:213], v[2:3], v[244:245]
	v_pk_fma_f32 v[4:5], v[214:215], v[4:5], v[246:247]
	v_lshl_add_u64 v[196:197], v[194:195], 0, v[198:199]
	global_store_dwordx4 v[196:197], v[2:5], off offset:192
	s_mov_b64 s[0:1], 0xc0
	s_mov_b64 s[52:53], 0xc0
	s_add_i32 s44, s44, 1
	s_mov_b64 s[98:99], s[54:55]
	s_mov_b64 s[0:1], 0

; __global__ void __launch_bounds__(NTHREADS, 2) fwd_megakernel(Params p_arg) {
;     ...
;       const float* gt = modl + (size_t)(brow >> 12) * 6144 + 5120;
; #pragma unroll
;       for (int n = 0; n < 4; ++n) {
;         const float4 g4 = *(const float4*)(gt + cofs + n * 16);
; #pragma unroll
;         for (int m = 0; m < 8; ++m) {
;           const size_t row = (size_t)brow + wr * 128 + m * 16 + fr;
;           float4 xo = *(const float4*)(pk->out + row * 1024 + cofs + n * 16);
;           xo.x += g4.x * acc[m][n][0]; xo.y += g4.y * acc[m][n][1]; xo.z += g4.z * acc[m][n][2]; xo.w += g4.w * acc[m][n][3];
;           *(float4*)(pk->out + row * 1024 + cofs + n * 16) = xo;
;         }
;         if (n == 1) __builtin_amdgcn_sched_barrier(0);
;       }
.LBB0_670:
	s_ashr_i32 s0, s20, 4
	v_or_b32_e32 v132, s21, v144
	s_mul_hi_i32 s1, s0, 0x6000
	s_mulk_i32 s0, 0x6000
	s_add_u32 s0, s12, s0
	v_ashrrev_i32_e32 v133, 31, v132
	s_addc_u32 s1, s13, s1
	v_lshlrev_b64 v[132:133], 2, v[132:133]
	v_lshl_add_u64 v[146:147], s[0:1], 0, v[132:133]
	s_mov_b64 s[0:1], 0x7105000
	v_lshl_add_u64 v[134:135], v[146:147], 0, s[0:1]
	s_load_dwordx2 s[0:1], s[4:5], 0x90
	v_lshl_add_u64 v[136:137], v[130:131], 0, s[6:7]
	s_waitcnt lgkmcnt(0)
	v_lshl_add_u64 v[138:139], s[0:1], 0, v[132:133]
	s_mov_b32 s0, 0x7105000
	v_add_co_u32_e32 v146, vcc, s0, v146
	v_lshlrev_b64 v[132:133], 12, v[136:137]
	s_nop 0
	v_addc_co_u32_e32 v147, vcc, 0, v147, vcc
	v_lshl_add_u64 v[136:137], v[138:139], 0, v[132:133]
	v_lshl_add_u64 v[180:181], v[138:139], 0, v[132:133]
	v_or_b32_e32 v196, 0x10000, v132
	v_mov_b32_e32 v197, v133
	v_lshl_add_u64 v[182:183], v[138:139], 0, v[196:197]
	v_or_b32_e32 v196, 0x20000, v132
	v_mov_b32_e32 v197, v133
	v_lshl_add_u64 v[184:185], v[138:139], 0, v[196:197]
	v_or_b32_e32 v196, 0x30000, v132
	v_mov_b32_e32 v197, v133
	v_lshl_add_u64 v[186:187], v[138:139], 0, v[196:197]
	v_or_b32_e32 v196, 0x40000, v132
	v_mov_b32_e32 v197, v133
	v_lshl_add_u64 v[188:189], v[138:139], 0, v[196:197]
	v_or_b32_e32 v196, 0x50000, v132
	v_mov_b32_e32 v197, v133
	v_lshl_add_u64 v[190:191], v[138:139], 0, v[196:197]
	v_or_b32_e32 v196, 0x60000, v132
	v_mov_b32_e32 v197, v133
	v_lshl_add_u64 v[192:193], v[138:139], 0, v[196:197]
	v_or_b32_e32 v196, 0x70000, v132
	v_mov_b32_e32 v197, v133
	v_lshl_add_u64 v[194:195], v[138:139], 0, v[196:197]
	global_load_dwordx4 v[200:203], v[134:135], off
	global_load_dwordx4 v[204:207], v[134:135], off offset:64
	global_load_dwordx4 v[208:211], v[134:135], off offset:128
	global_load_dwordx4 v[212:215], v[134:135], off offset:192
	global_load_dwordx4 v[216:219], v[180:181], off
	global_load_dwordx4 v[220:223], v[182:183], off
	global_load_dwordx4 v[224:227], v[184:185], off
	global_load_dwordx4 v[228:231], v[186:187], off
	global_load_dwordx4 v[232:235], v[188:189], off
	global_load_dwordx4 v[236:239], v[190:191], off
	global_load_dwordx4 v[240:243], v[192:193], off
	global_load_dwordx4 v[244:247], v[194:195], off
	s_waitcnt vmcnt(7)
	v_pk_fma_f32 v[126:127], v[200:201], v[126:127], v[216:217]
	v_pk_fma_f32 v[128:129], v[202:203], v[128:129], v[218:219]
	global_store_dwordx4 v[180:181], v[126:129], off
	global_load_dwordx4 v[216:219], v[180:181], off offset:64
	s_waitcnt vmcnt(8)
	v_pk_fma_f32 v[122:123], v[200:201], v[122:123], v[220:221]
	v_pk_fma_f32 v[124:125], v[202:203], v[124:125], v[222:223]
	global_store_dwordx4 v[182:183], v[122:125], off
	global_load_dwordx4 v[220:223], v[182:183], off offset:64
	s_waitcnt vmcnt(9)
	v_pk_fma_f32 v[118:119], v[200:201], v[118:119], v[224:225]
	v_pk_fma_f32 v[120:121], v[202:203], v[120:121], v[226:227]
	global_store_dwordx4 v[184:185], v[118:121], off
	global_load_dwordx4 v[224:227], v[184:185], off offset:64
	s_waitcnt vmcnt(10)
	v_pk_fma_f32 v[110:111], v[200:201], v[110:111], v[228:229]
	v_pk_fma_f32 v[112:113], v[202:203], v[112:113], v[230:231]
	global_store_dwordx4 v[186:187], v[110:113], off
	global_load_dwordx4 v[228:231], v[186:187], off offset:64
	s_waitcnt vmcnt(11)
	v_pk_fma_f32 v[114:115], v[200:201], v[114:115], v[232:233]
	v_pk_fma_f32 v[116:117], v[202:203], v[116:117], v[234:235]
	global_store_dwordx4 v[188:189], v[114:117], off
	global_load_dwordx4 v[232:235], v[188:189], off offset:64
	s_waitcnt vmcnt(12)
	v_pk_fma_f32 v[106:107], v[200:201], v[106:107], v[236:237]
	v_pk_fma_f32 v[108:109], v[202:203], v[108:109], v[238:239]
	global_store_dwordx4 v[190:191], v[106:109], off
	global_load_dwordx4 v[236:239], v[190:191], off offset:64
	s_waitcnt vmcnt(13)
	v_pk_fma_f32 v[102:103], v[200:201], v[102:103], v[240:241]
	v_pk_fma_f32 v[104:105], v[202:203], v[104:105], v[242:243]
	global_store_dwordx4 v[192:193], v[102:105], off
	global_load_dwordx4 v[240:243], v[192:193], off offset:64
	s_waitcnt vmcnt(14)
	v_pk_fma_f32 v[98:99], v[200:201], v[98:99], v[244:245]
	v_pk_fma_f32 v[100:101], v[202:203], v[100:101], v[246:247]
	global_store_dwordx4 v[194:195], v[98:101], off
	global_load_dwordx4 v[244:247], v[194:195], off offset:64
	s_waitcnt vmcnt(14)
	v_pk_fma_f32 v[86:87], v[204:205], v[86:87], v[216:217]
	v_pk_fma_f32 v[88:89], v[206:207], v[88:89], v[218:219]
	global_store_dwordx4 v[180:181], v[86:89], off offset:64
	global_load_dwordx4 v[216:219], v[180:181], off offset:128
	s_waitcnt vmcnt(14)
	v_pk_fma_f32 v[90:91], v[204:205], v[90:91], v[220:221]
	v_pk_fma_f32 v[92:93], v[206:207], v[92:93], v[222:223]
	global_store_dwordx4 v[182:183], v[90:93], off offset:64
	global_load_dwordx4 v[220:223], v[182:183], off offset:128
	s_waitcnt vmcnt(14)
	v_pk_fma_f32 v[94:95], v[204:205], v[94:95], v[224:225]
	v_pk_fma_f32 v[96:97], v[206:207], v[96:97], v[226:227]
	global_store_dwordx4 v[184:185], v[94:97], off offset:64
	global_load_dwordx4 v[224:227], v[184:185], off offset:128
	s_waitcnt vmcnt(14)
; __global__ void __launch_bounds__(NTHREADS, 2) fwd_megakernel(Params p_arg) {
;     ...
;       const float* gt = modl + (size_t)(brow >> 12) * 6144 + 5120;
; #pragma unroll
;       for (int n = 0; n < 4; ++n) {
;         const float4 g4 = *(const float4*)(gt + cofs + n * 16);
; #pragma unroll
;         for (int m = 0; m < 8; ++m) {
;           const size_t row = (size_t)brow + wr * 128 + m * 16 + fr;
;           float4 xo = *(const float4*)(pk->out + row * 1024 + cofs + n * 16);
;           xo.x += g4.x * acc[m][n][0]; xo.y += g4.y * acc[m][n][1]; xo.z += g4.z * acc[m][n][2]; xo.w += g4.w * acc[m][n][3];
;           *(float4*)(pk->out + row * 1024 + cofs + n * 16) = xo;
;         }
;         if (n == 1) __builtin_amdgcn_sched_barrier(0);
;       }
	v_pk_fma_f32 v[82:83], v[204:205], v[82:83], v[228:229]
	v_pk_fma_f32 v[84:85], v[206:207], v[84:85], v[230:231]
	global_store_dwordx4 v[186:187], v[82:85], off offset:64
	global_load_dwordx4 v[228:231], v[186:187], off offset:128
	s_waitcnt vmcnt(14)
	v_pk_fma_f32 v[78:79], v[204:205], v[78:79], v[232:233]
	v_pk_fma_f32 v[80:81], v[206:207], v[80:81], v[234:235]
	global_store_dwordx4 v[188:189], v[78:81], off offset:64
	global_load_dwordx4 v[232:235], v[188:189], off offset:128
	s_waitcnt vmcnt(14)
	v_pk_fma_f32 v[74:75], v[204:205], v[74:75], v[236:237]
	v_pk_fma_f32 v[76:77], v[206:207], v[76:77], v[238:239]
	global_store_dwordx4 v[190:191], v[74:77], off offset:64
	global_load_dwordx4 v[236:239], v[190:191], off offset:128
	s_waitcnt vmcnt(14)
	v_pk_fma_f32 v[70:71], v[204:205], v[70:71], v[240:241]
	v_pk_fma_f32 v[72:73], v[206:207], v[72:73], v[242:243]
	global_store_dwordx4 v[192:193], v[70:73], off offset:64
	global_load_dwordx4 v[240:243], v[192:193], off offset:128
	s_waitcnt vmcnt(14)
	v_pk_fma_f32 v[66:67], v[204:205], v[66:67], v[244:245]
	v_pk_fma_f32 v[68:69], v[206:207], v[68:69], v[246:247]
	global_store_dwordx4 v[194:195], v[66:69], off offset:64
	global_load_dwordx4 v[244:247], v[194:195], off offset:128
	s_waitcnt vmcnt(14)
	v_pk_fma_f32 v[62:63], v[208:209], v[62:63], v[216:217]
	v_pk_fma_f32 v[64:65], v[210:211], v[64:65], v[218:219]
	global_store_dwordx4 v[180:181], v[62:65], off offset:128
	global_load_dwordx4 v[216:219], v[180:181], off offset:192
	s_waitcnt vmcnt(14)
	v_pk_fma_f32 v[58:59], v[208:209], v[58:59], v[220:221]
	v_pk_fma_f32 v[60:61], v[210:211], v[60:61], v[222:223]
	global_store_dwordx4 v[182:183], v[58:61], off offset:128
	global_load_dwordx4 v[220:223], v[182:183], off offset:192
	s_waitcnt vmcnt(14)
	v_pk_fma_f32 v[54:55], v[208:209], v[54:55], v[224:225]
	v_pk_fma_f32 v[56:57], v[210:211], v[56:57], v[226:227]
	global_store_dwordx4 v[184:185], v[54:57], off offset:128
	global_load_dwordx4 v[224:227], v[184:185], off offset:192
	s_waitcnt vmcnt(14)
	v_pk_fma_f32 v[46:47], v[208:209], v[46:47], v[228:229]
	v_pk_fma_f32 v[48:49], v[210:211], v[48:49], v[230:231]
	global_store_dwordx4 v[186:187], v[46:49], off offset:128
	global_load_dwordx4 v[228:231], v[186:187], off offset:192
	s_waitcnt vmcnt(14)
	v_pk_fma_f32 v[50:51], v[208:209], v[50:51], v[232:233]
	v_pk_fma_f32 v[52:53], v[210:211], v[52:53], v[234:235]
	global_store_dwordx4 v[188:189], v[50:53], off offset:128
	global_load_dwordx4 v[232:235], v[188:189], off offset:192
	s_waitcnt vmcnt(14)
	v_pk_fma_f32 v[42:43], v[208:209], v[42:43], v[236:237]
	v_pk_fma_f32 v[44:45], v[210:211], v[44:45], v[238:239]
	global_store_dwordx4 v[190:191], v[42:45], off offset:128
	global_load_dwordx4 v[236:239], v[190:191], off offset:192
	s_waitcnt vmcnt(14)
	v_pk_fma_f32 v[38:39], v[208:209], v[38:39], v[240:241]
	v_pk_fma_f32 v[40:41], v[210:211], v[40:41], v[242:243]
	global_store_dwordx4 v[192:193], v[38:41], off offset:128
	global_load_dwordx4 v[240:243], v[192:193], off offset:192
	s_waitcnt vmcnt(14)
	v_pk_fma_f32 v[34:35], v[208:209], v[34:35], v[244:245]
	v_pk_fma_f32 v[36:37], v[210:211], v[36:37], v[246:247]
	global_store_dwordx4 v[194:195], v[34:37], off offset:128
	global_load_dwordx4 v[244:247], v[194:195], off offset:192
	s_waitcnt vmcnt(14)
	v_pk_fma_f32 v[22:23], v[212:213], v[22:23], v[216:217]
	v_pk_fma_f32 v[24:25], v[214:215], v[24:25], v[218:219]
	global_store_dwordx4 v[180:181], v[22:25], off offset:192
	s_waitcnt vmcnt(13)
	v_pk_fma_f32 v[26:27], v[212:213], v[26:27], v[220:221]
	v_pk_fma_f32 v[28:29], v[214:215], v[28:29], v[222:223]
	global_store_dwordx4 v[182:183], v[26:29], off offset:192
	s_waitcnt vmcnt(12)
	v_pk_fma_f32 v[30:31], v[212:213], v[30:31], v[224:225]
	v_pk_fma_f32 v[32:33], v[214:215], v[32:33], v[226:227]
	global_store_dwordx4 v[184:185], v[30:33], off offset:192
	s_waitcnt vmcnt(11)
	v_pk_fma_f32 v[18:19], v[212:213], v[18:19], v[228:229]
	v_pk_fma_f32 v[20:21], v[214:215], v[20:21], v[230:231]
	global_store_dwordx4 v[186:187], v[18:21], off offset:192
	s_waitcnt vmcnt(10)
	v_pk_fma_f32 v[14:15], v[212:213], v[14:15], v[232:233]
	v_pk_fma_f32 v[16:17], v[214:215], v[16:17], v[234:235]
	global_store_dwordx4 v[188:189], v[14:17], off offset:192
	s_waitcnt vmcnt(9)
	v_pk_fma_f32 v[10:11], v[212:213], v[10:11], v[236:237]
	v_pk_fma_f32 v[12:13], v[214:215], v[12:13], v[238:239]
	global_store_dwordx4 v[190:191], v[10:13], off offset:192
	s_waitcnt vmcnt(8)
	v_pk_fma_f32 v[6:7], v[212:213], v[6:7], v[240:241]
	v_pk_fma_f32 v[8:9], v[214:215], v[8:9], v[242:243]
	global_store_dwordx4 v[192:193], v[6:9], off offset:192
	s_waitcnt vmcnt(7)
	v_pk_fma_f32 v[2:3], v[212:213], v[2:3], v[244:245]
	v_pk_fma_f32 v[4:5], v[214:215], v[4:5], v[246:247]
	global_store_dwordx4 v[194:195], v[2:5], off offset:192
	s_add_i32 s19, s19, 1
	s_mov_b64 s[0:1], 0
